# SGU output stores marked non-temporal (cache-policy hint only)
# baseline (speedup 1.0000x reference)
.LBB0_123:
	v_lshl_add_u64 v[34:35], v[140:141], 0, s[72:73]
	global_load_dwordx4 v[34:37], v[34:35], off
	v_lshlrev_b32_e32 v38, 16, v208
	v_mul_f32_e32 v39, 0x3d372713, v38
	v_mul_f32_e32 v39, v39, v38
	v_fma_f32 v39, v39, v38, v38
	v_mul_f32_e32 v39, 0xbfcc422a, v39
	v_mul_f32_e32 v39, 0x3fb8aa3b, v39
	v_exp_f32_e32 v39, v39
	v_lshl_add_u64 v[42:43], v[120:121], 0, s[74:75]
	s_add_i32 s48, s48, 1
	s_mov_b64 s[56:57], 0x10000
	v_add_f32_e32 v39, 1.0, v39
	v_rcp_f32_e32 v39, v39
	v_lshl_add_u64 v[142:143], v[142:143], 0, s[56:57]
	v_lshl_add_u64 v[140:141], v[140:141], 0, s[90:91]
	v_lshl_add_u64 v[138:139], v[138:139], 0, s[90:91]
	v_mul_f32_e32 v38, v39, v38
	v_lshl_add_u64 v[136:137], v[136:137], 0, s[90:91]
	v_lshl_add_u64 v[134:135], v[134:135], 0, s[90:91]
	v_lshl_add_u64 v[132:133], v[132:133], 0, s[90:91]
	v_lshl_add_u64 v[130:131], v[130:131], 0, s[90:91]
	v_lshl_add_u64 v[128:129], v[128:129], 0, s[90:91]
	v_lshl_add_u64 v[126:127], v[126:127], 0, s[90:91]
	v_lshl_add_u64 v[124:125], v[124:125], 0, s[90:91]
	s_waitcnt vmcnt(0)
	v_add_f32_e32 v30, v34, v30
	v_mul_f32_e32 v30, v38, v30
	v_cvt_pk_bf16_f32 v30, v30, s0
	v_lshl_add_u64 v[38:39], v[108:109], 0, s[74:75]
	flat_store_short v[38:39], v30 nt
	v_lshlrev_b32_e32 v30, 16, v207
	v_mul_f32_e32 v40, 0x3d372713, v30
	v_mul_f32_e32 v40, v40, v30
	v_fma_f32 v40, v40, v30, v30
	v_mul_f32_e32 v40, 0xbfcc422a, v40
	v_mul_f32_e32 v40, 0x3fb8aa3b, v40
	v_exp_f32_e32 v40, v40
	v_add_f32_e32 v26, v26, v34
	v_add_f32_e32 v22, v22, v34
	v_add_f32_e32 v18, v18, v34
	v_add_f32_e32 v40, 1.0, v40
	v_rcp_f32_e32 v40, v40
	v_add_f32_e32 v14, v14, v34
	v_add_f32_e32 v10, v10, v34
	v_add_f32_e32 v6, v6, v34
	v_mul_f32_e32 v30, v40, v30
	v_mul_f32_e32 v26, v30, v26
	v_cvt_pk_bf16_f32 v26, v26, s0
	flat_store_short v[38:39], v26 offset:32 nt
	v_lshlrev_b32_e32 v26, 16, v206
	v_mul_f32_e32 v30, 0x3d372713, v26
	v_mul_f32_e32 v30, v30, v26
	v_fma_f32 v30, v30, v26, v26
	v_mul_f32_e32 v30, 0xbfcc422a, v30
	v_mul_f32_e32 v30, 0x3fb8aa3b, v30
	v_exp_f32_e32 v30, v30
	v_lshl_add_u64 v[40:41], v[118:119], 0, s[74:75]
	v_add_f32_e32 v2, v2, v34
	v_add_f32_e32 v3, v3, v35
	v_add_f32_e32 v30, 1.0, v30
	v_rcp_f32_e32 v30, v30
	v_add_f32_e32 v4, v4, v36
	s_add_u32 s74, s74, 0x100
	s_addc_u32 s75, s75, 0
	v_mul_f32_e32 v26, v30, v26
	v_mul_f32_e32 v22, v26, v22
	v_cvt_pk_bf16_f32 v22, v22, s0
	flat_store_short v[38:39], v22 offset:64 nt
	v_lshlrev_b32_e32 v22, 16, v205
	v_mul_f32_e32 v26, 0x3d372713, v22
	v_mul_f32_e32 v26, v26, v22
	v_fma_f32 v26, v26, v22, v22
	v_mul_f32_e32 v26, 0xbfcc422a, v26
	v_mul_f32_e32 v26, 0x3fb8aa3b, v26
	v_exp_f32_e32 v26, v26
	s_cmpk_eq_i32 s74, 0x400
	v_add_f32_e32 v26, 1.0, v26
	v_rcp_f32_e32 v26, v26
	s_nop 0
	v_mul_f32_e32 v22, v26, v22
	v_mul_f32_e32 v18, v22, v18
	v_cvt_pk_bf16_f32 v18, v18, s0
	flat_store_short v[40:41], v18 nt
	v_lshlrev_b32_e32 v18, 16, v204
	v_mul_f32_e32 v22, 0x3d372713, v18
	v_mul_f32_e32 v22, v22, v18
	v_fma_f32 v22, v22, v18, v18
	v_mul_f32_e32 v22, 0xbfcc422a, v22
	v_mul_f32_e32 v22, 0x3fb8aa3b, v22
	v_exp_f32_e32 v22, v22
	s_nop 0
	v_add_f32_e32 v22, 1.0, v22
	v_rcp_f32_e32 v22, v22
	s_nop 0
	v_mul_f32_e32 v18, v22, v18
	v_mul_f32_e32 v14, v18, v14
	v_cvt_pk_bf16_f32 v14, v14, s0
	flat_store_short v[38:39], v14 offset:128 nt
	v_lshlrev_b32_e32 v14, 16, v203
	v_mul_f32_e32 v18, 0x3d372713, v14
	v_mul_f32_e32 v18, v18, v14
	v_fma_f32 v18, v18, v14, v14
	v_mul_f32_e32 v18, 0xbfcc422a, v18
	v_mul_f32_e32 v18, 0x3fb8aa3b, v18
	v_exp_f32_e32 v18, v18
	s_nop 0
	v_add_f32_e32 v18, 1.0, v18
	v_rcp_f32_e32 v18, v18
	s_nop 0
	v_mul_f32_e32 v14, v18, v14
	v_mul_f32_e32 v10, v14, v10
	v_cvt_pk_bf16_f32 v10, v10, s0
	flat_store_short v[38:39], v10 offset:160 nt
	v_lshlrev_b32_e32 v10, 16, v202
	v_mul_f32_e32 v14, 0x3d372713, v10
	v_mul_f32_e32 v14, v14, v10
	v_fma_f32 v14, v14, v10, v10
	v_mul_f32_e32 v14, 0xbfcc422a, v14
	v_mul_f32_e32 v14, 0x3fb8aa3b, v14
	v_exp_f32_e32 v14, v14
	s_nop 0
	v_add_f32_e32 v14, 1.0, v14
	v_rcp_f32_e32 v14, v14
	s_nop 0
	v_mul_f32_e32 v10, v14, v10
	v_mul_f32_e32 v6, v10, v6
	v_cvt_pk_bf16_f32 v6, v6, s0
	flat_store_short v[38:39], v6 offset:192 nt
	v_lshlrev_b32_e32 v6, 16, v201
	v_mul_f32_e32 v10, 0x3d372713, v6
	v_mul_f32_e32 v10, v10, v6
	v_fma_f32 v10, v10, v6, v6
	v_mul_f32_e32 v10, 0xbfcc422a, v10
	v_mul_f32_e32 v10, 0x3fb8aa3b, v10
	v_exp_f32_e32 v10, v10
	s_nop 0
	v_add_f32_e32 v10, 1.0, v10
	v_rcp_f32_e32 v10, v10
	s_nop 0
	v_mul_f32_e32 v6, v10, v6
	v_mul_f32_e32 v2, v6, v2
	v_cvt_pk_bf16_f32 v2, v2, s0
	flat_store_short v[42:43], v2 nt
	v_lshlrev_b32_e32 v2, 16, v200
	v_mul_f32_e32 v6, 0x3d372713, v2
	v_mul_f32_e32 v6, v6, v2
	v_fma_f32 v6, v6, v2, v2
	v_mul_f32_e32 v6, 0xbfcc422a, v6
	v_mul_f32_e32 v6, 0x3fb8aa3b, v6
	v_exp_f32_e32 v6, v6
	s_nop 0
	v_add_f32_e32 v6, 1.0, v6
	v_rcp_f32_e32 v6, v6
	s_nop 0
	v_mul_f32_e32 v2, v6, v2
	v_add_f32_e32 v6, v31, v35
	v_mul_f32_e32 v2, v2, v6
	v_cvt_pk_bf16_f32 v2, v2, s0
	flat_store_short v[38:39], v2 offset:2048 nt
	v_lshlrev_b32_e32 v2, 16, v199
	v_mul_f32_e32 v6, 0x3d372713, v2
	v_mul_f32_e32 v6, v6, v2
	v_fma_f32 v6, v6, v2, v2
	v_mul_f32_e32 v6, 0xbfcc422a, v6
	v_mul_f32_e32 v6, 0x3fb8aa3b, v6
	v_exp_f32_e32 v6, v6
	s_nop 0
	v_add_f32_e32 v6, 1.0, v6
	v_rcp_f32_e32 v6, v6
	s_nop 0
	v_mul_f32_e32 v2, v6, v2
	v_add_f32_e32 v6, v27, v35
	v_mul_f32_e32 v2, v2, v6
	v_cvt_pk_bf16_f32 v2, v2, s0
	flat_store_short v[38:39], v2 offset:2080 nt
	v_lshlrev_b32_e32 v2, 16, v198
	v_mul_f32_e32 v6, 0x3d372713, v2
	v_mul_f32_e32 v6, v6, v2
	v_fma_f32 v6, v6, v2, v2
	v_mul_f32_e32 v6, 0xbfcc422a, v6
	v_mul_f32_e32 v6, 0x3fb8aa3b, v6
	v_exp_f32_e32 v6, v6
	s_nop 0
	v_add_f32_e32 v6, 1.0, v6
	v_rcp_f32_e32 v6, v6
	s_nop 0
	v_mul_f32_e32 v2, v6, v2
	v_add_f32_e32 v6, v23, v35
	v_mul_f32_e32 v2, v2, v6
	v_cvt_pk_bf16_f32 v2, v2, s0
	flat_store_short v[38:39], v2 offset:2112 nt
	v_lshlrev_b32_e32 v2, 16, v197
	v_mul_f32_e32 v6, 0x3d372713, v2
	v_mul_f32_e32 v6, v6, v2
	v_fma_f32 v6, v6, v2, v2
	v_mul_f32_e32 v6, 0xbfcc422a, v6
	v_mul_f32_e32 v6, 0x3fb8aa3b, v6
	v_exp_f32_e32 v6, v6
	s_nop 0
	v_add_f32_e32 v6, 1.0, v6
	v_rcp_f32_e32 v6, v6
	s_nop 0
	v_mul_f32_e32 v2, v6, v2
	v_add_f32_e32 v6, v19, v35
	v_mul_f32_e32 v2, v2, v6
	v_cvt_pk_bf16_f32 v2, v2, s0
	flat_store_short v[40:41], v2 offset:2048 nt
	v_lshlrev_b32_e32 v2, 16, v196
	v_mul_f32_e32 v6, 0x3d372713, v2
	v_mul_f32_e32 v6, v6, v2
	v_fma_f32 v6, v6, v2, v2
	v_mul_f32_e32 v6, 0xbfcc422a, v6
	v_mul_f32_e32 v6, 0x3fb8aa3b, v6
	v_exp_f32_e32 v6, v6
	s_nop 0
	v_add_f32_e32 v6, 1.0, v6
	v_rcp_f32_e32 v6, v6
	s_nop 0
	v_mul_f32_e32 v2, v6, v2
	v_add_f32_e32 v6, v15, v35
	v_mul_f32_e32 v2, v2, v6
	v_cvt_pk_bf16_f32 v2, v2, s0
	flat_store_short v[38:39], v2 offset:2176 nt
	v_lshlrev_b32_e32 v2, 16, v195
	v_mul_f32_e32 v6, 0x3d372713, v2
	v_mul_f32_e32 v6, v6, v2
	v_fma_f32 v6, v6, v2, v2
	v_mul_f32_e32 v6, 0xbfcc422a, v6
	v_mul_f32_e32 v6, 0x3fb8aa3b, v6
	v_exp_f32_e32 v6, v6
	s_nop 0
	v_add_f32_e32 v6, 1.0, v6
	v_rcp_f32_e32 v6, v6
	s_nop 0
	v_mul_f32_e32 v2, v6, v2
	v_add_f32_e32 v6, v11, v35
	v_mul_f32_e32 v2, v2, v6
	v_cvt_pk_bf16_f32 v2, v2, s0
	flat_store_short v[38:39], v2 offset:2208 nt
	v_lshlrev_b32_e32 v2, 16, v194
	v_mul_f32_e32 v6, 0x3d372713, v2
	v_mul_f32_e32 v6, v6, v2
	v_fma_f32 v6, v6, v2, v2
	v_mul_f32_e32 v6, 0xbfcc422a, v6
	v_mul_f32_e32 v6, 0x3fb8aa3b, v6
	v_exp_f32_e32 v6, v6
	s_nop 0
	v_add_f32_e32 v6, 1.0, v6
	v_rcp_f32_e32 v6, v6
	s_nop 0
	v_mul_f32_e32 v2, v6, v2
	v_add_f32_e32 v6, v7, v35
	v_mul_f32_e32 v2, v2, v6
	v_cvt_pk_bf16_f32 v2, v2, s0
	flat_store_short v[38:39], v2 offset:2240 nt
	v_lshlrev_b32_e32 v2, 16, v193
	v_mul_f32_e32 v6, 0x3d372713, v2
	v_mul_f32_e32 v6, v6, v2
	v_fma_f32 v6, v6, v2, v2
	v_mul_f32_e32 v6, 0xbfcc422a, v6
	v_mul_f32_e32 v6, 0x3fb8aa3b, v6
	v_exp_f32_e32 v6, v6
	s_nop 0
	v_add_f32_e32 v6, 1.0, v6
	v_rcp_f32_e32 v6, v6
	s_nop 0
	v_mul_f32_e32 v2, v6, v2
	v_mul_f32_e32 v2, v2, v3
	v_cvt_pk_bf16_f32 v2, v2, s0
	flat_store_short v[42:43], v2 offset:2048 nt
	v_lshlrev_b32_e32 v2, 16, v192
	v_mul_f32_e32 v3, 0x3d372713, v2
	v_mul_f32_e32 v3, v3, v2
	v_fma_f32 v3, v3, v2, v2
	v_mul_f32_e32 v3, 0xbfcc422a, v3
	v_mul_f32_e32 v3, 0x3fb8aa3b, v3
	v_exp_f32_e32 v3, v3
	s_nop 0
	v_add_f32_e32 v3, 1.0, v3
	v_rcp_f32_e32 v3, v3
	s_nop 0
	v_mul_f32_e32 v2, v3, v2
	v_add_f32_e32 v3, v32, v36
	v_mul_f32_e32 v2, v2, v3
	v_cvt_pk_bf16_f32 v6, v2, s0
	v_add_co_u32_e32 v2, vcc, s52, v38
	s_nop 1
	v_addc_co_u32_e32 v3, vcc, 0, v39, vcc
	flat_store_short v[2:3], v6 nt
	v_lshlrev_b32_e32 v6, 16, v191
	v_mul_f32_e32 v7, 0x3d372713, v6
	v_mul_f32_e32 v7, v7, v6
	v_fma_f32 v7, v7, v6, v6
	v_mul_f32_e32 v7, 0xbfcc422a, v7
	v_mul_f32_e32 v7, 0x3fb8aa3b, v7
	v_exp_f32_e32 v7, v7
	v_add_co_u32_e32 v10, vcc, s52, v40
	v_add_f32_e32 v7, 1.0, v7
	v_rcp_f32_e32 v7, v7
	v_addc_co_u32_e32 v11, vcc, 0, v41, vcc
	v_mul_f32_e32 v6, v7, v6
	v_add_f32_e32 v7, v28, v36
	v_mul_f32_e32 v6, v6, v7
	v_cvt_pk_bf16_f32 v6, v6, s0
	flat_store_short v[2:3], v6 offset:32 nt
	v_lshlrev_b32_e32 v6, 16, v190
	v_mul_f32_e32 v7, 0x3d372713, v6
	v_mul_f32_e32 v7, v7, v6
	v_fma_f32 v7, v7, v6, v6
	v_mul_f32_e32 v7, 0xbfcc422a, v7
	v_mul_f32_e32 v7, 0x3fb8aa3b, v7
	v_exp_f32_e32 v7, v7
	s_nop 0
	v_add_f32_e32 v7, 1.0, v7
	v_rcp_f32_e32 v7, v7
	s_nop 0
	v_mul_f32_e32 v6, v7, v6
	v_add_f32_e32 v7, v24, v36
	v_mul_f32_e32 v6, v6, v7
	v_cvt_pk_bf16_f32 v6, v6, s0
	flat_store_short v[2:3], v6 offset:64 nt
	v_lshlrev_b32_e32 v6, 16, v189
	v_mul_f32_e32 v7, 0x3d372713, v6
	v_mul_f32_e32 v7, v7, v6
	v_fma_f32 v7, v7, v6, v6
	v_mul_f32_e32 v7, 0xbfcc422a, v7
	v_mul_f32_e32 v7, 0x3fb8aa3b, v7
	v_exp_f32_e32 v7, v7
	s_nop 0
	v_add_f32_e32 v7, 1.0, v7
	v_rcp_f32_e32 v7, v7
	s_nop 0
	v_mul_f32_e32 v6, v7, v6
	v_add_f32_e32 v7, v20, v36
	v_mul_f32_e32 v6, v6, v7
	v_cvt_pk_bf16_f32 v6, v6, s0
	flat_store_short v[10:11], v6 nt
	v_lshlrev_b32_e32 v6, 16, v188
	v_mul_f32_e32 v7, 0x3d372713, v6
	v_mul_f32_e32 v7, v7, v6
	v_fma_f32 v7, v7, v6, v6
	v_mul_f32_e32 v7, 0xbfcc422a, v7
	v_mul_f32_e32 v7, 0x3fb8aa3b, v7
	v_exp_f32_e32 v7, v7
	s_nop 0
	v_add_f32_e32 v7, 1.0, v7
	v_rcp_f32_e32 v7, v7
	s_nop 0
	v_mul_f32_e32 v6, v7, v6
	v_add_f32_e32 v7, v16, v36
	v_mul_f32_e32 v6, v6, v7
	v_cvt_pk_bf16_f32 v6, v6, s0
	flat_store_short v[2:3], v6 offset:128 nt
	v_lshlrev_b32_e32 v6, 16, v187
	v_mul_f32_e32 v7, 0x3d372713, v6
	v_mul_f32_e32 v7, v7, v6
	v_fma_f32 v7, v7, v6, v6
	v_mul_f32_e32 v7, 0xbfcc422a, v7
	v_mul_f32_e32 v7, 0x3fb8aa3b, v7
	v_exp_f32_e32 v7, v7
	s_nop 0
	v_add_f32_e32 v7, 1.0, v7
	v_rcp_f32_e32 v7, v7
	s_nop 0
	v_mul_f32_e32 v6, v7, v6
	v_add_f32_e32 v7, v12, v36
	v_mul_f32_e32 v6, v6, v7
	v_cvt_pk_bf16_f32 v6, v6, s0
	flat_store_short v[2:3], v6 offset:160 nt
	v_lshlrev_b32_e32 v6, 16, v186
	v_mul_f32_e32 v7, 0x3d372713, v6
	v_mul_f32_e32 v7, v7, v6
	v_fma_f32 v7, v7, v6, v6
	v_mul_f32_e32 v7, 0xbfcc422a, v7
	v_mul_f32_e32 v7, 0x3fb8aa3b, v7
	v_exp_f32_e32 v7, v7
	s_nop 0
	v_add_f32_e32 v7, 1.0, v7
	v_rcp_f32_e32 v7, v7
	s_nop 0
	v_mul_f32_e32 v6, v7, v6
	v_add_f32_e32 v7, v8, v36
	v_mul_f32_e32 v6, v6, v7
	v_cvt_pk_bf16_f32 v6, v6, s0
	flat_store_short v[2:3], v6 offset:192 nt
	v_lshlrev_b32_e32 v6, 16, v185
	v_mul_f32_e32 v7, 0x3d372713, v6
	v_mul_f32_e32 v7, v7, v6
	v_fma_f32 v7, v7, v6, v6
	v_mul_f32_e32 v7, 0xbfcc422a, v7
	v_mul_f32_e32 v7, 0x3fb8aa3b, v7
	v_exp_f32_e32 v7, v7
	s_nop 0
	v_add_f32_e32 v7, 1.0, v7
	v_rcp_f32_e32 v7, v7
	s_nop 0
	v_mul_f32_e32 v6, v7, v6
	v_mul_f32_e32 v4, v6, v4
	v_add_co_u32_e32 v6, vcc, s52, v42
	v_cvt_pk_bf16_f32 v4, v4, s0
	s_nop 0
	v_addc_co_u32_e32 v7, vcc, 0, v43, vcc
	flat_store_short v[6:7], v4 nt
	v_lshlrev_b32_e32 v4, 16, v184
	v_mul_f32_e32 v8, 0x3d372713, v4
	v_mul_f32_e32 v8, v8, v4
	v_fma_f32 v8, v8, v4, v4
	v_mul_f32_e32 v8, 0xbfcc422a, v8
	v_mul_f32_e32 v8, 0x3fb8aa3b, v8
	v_exp_f32_e32 v8, v8
	s_nop 0
	v_add_f32_e32 v8, 1.0, v8
	v_rcp_f32_e32 v8, v8
	s_nop 0
	v_mul_f32_e32 v4, v8, v4
	v_add_f32_e32 v8, v33, v37
	v_mul_f32_e32 v4, v4, v8
	v_cvt_pk_bf16_f32 v4, v4, s0
	flat_store_short v[2:3], v4 offset:2048 nt
	v_lshlrev_b32_e32 v4, 16, v183
	v_mul_f32_e32 v8, 0x3d372713, v4
	v_mul_f32_e32 v8, v8, v4
	v_fma_f32 v8, v8, v4, v4
	v_mul_f32_e32 v8, 0xbfcc422a, v8
	v_mul_f32_e32 v8, 0x3fb8aa3b, v8
	v_exp_f32_e32 v8, v8
	s_nop 0
	v_add_f32_e32 v8, 1.0, v8
	v_rcp_f32_e32 v8, v8
	s_nop 0
	v_mul_f32_e32 v4, v8, v4
	v_add_f32_e32 v8, v29, v37
	v_mul_f32_e32 v4, v4, v8
	v_cvt_pk_bf16_f32 v4, v4, s0
	flat_store_short v[2:3], v4 offset:2080 nt
	v_lshlrev_b32_e32 v4, 16, v182
	v_mul_f32_e32 v8, 0x3d372713, v4
	v_mul_f32_e32 v8, v8, v4
	v_fma_f32 v8, v8, v4, v4
	v_mul_f32_e32 v8, 0xbfcc422a, v8
	v_mul_f32_e32 v8, 0x3fb8aa3b, v8
	v_exp_f32_e32 v8, v8
	s_nop 0
	v_add_f32_e32 v8, 1.0, v8
	v_rcp_f32_e32 v8, v8
	s_nop 0
	v_mul_f32_e32 v4, v8, v4
	v_add_f32_e32 v8, v25, v37
	v_mul_f32_e32 v4, v4, v8
	v_cvt_pk_bf16_f32 v4, v4, s0
	flat_store_short v[2:3], v4 offset:2112 nt
	v_lshlrev_b32_e32 v4, 16, v181
	v_mul_f32_e32 v8, 0x3d372713, v4
	v_mul_f32_e32 v8, v8, v4
	v_fma_f32 v8, v8, v4, v4
	v_mul_f32_e32 v8, 0xbfcc422a, v8
	v_mul_f32_e32 v8, 0x3fb8aa3b, v8
	v_exp_f32_e32 v8, v8
	s_nop 0
	v_add_f32_e32 v8, 1.0, v8
	v_rcp_f32_e32 v8, v8
	s_nop 0
	v_mul_f32_e32 v4, v8, v4
	v_add_f32_e32 v8, v21, v37
	v_mul_f32_e32 v4, v4, v8
	v_cvt_pk_bf16_f32 v4, v4, s0
	flat_store_short v[10:11], v4 offset:2048 nt
	v_lshlrev_b32_e32 v4, 16, v180
	v_mul_f32_e32 v8, 0x3d372713, v4
	v_mul_f32_e32 v8, v8, v4
	v_fma_f32 v8, v8, v4, v4
	v_mul_f32_e32 v8, 0xbfcc422a, v8
	v_mul_f32_e32 v8, 0x3fb8aa3b, v8
	v_exp_f32_e32 v8, v8
	s_nop 0
	v_add_f32_e32 v8, 1.0, v8
	v_rcp_f32_e32 v8, v8
	s_nop 0
	v_mul_f32_e32 v4, v8, v4
	v_add_f32_e32 v8, v17, v37
	v_mul_f32_e32 v4, v4, v8
	v_cvt_pk_bf16_f32 v4, v4, s0
	flat_store_short v[2:3], v4 offset:2176 nt
	v_lshlrev_b32_e32 v4, 16, v179
	v_mul_f32_e32 v8, 0x3d372713, v4
	v_mul_f32_e32 v8, v8, v4
	v_fma_f32 v8, v8, v4, v4
	v_mul_f32_e32 v8, 0xbfcc422a, v8
	v_mul_f32_e32 v8, 0x3fb8aa3b, v8
	v_exp_f32_e32 v8, v8
	s_nop 0
	v_add_f32_e32 v8, 1.0, v8
	v_rcp_f32_e32 v8, v8
	s_nop 0
	v_mul_f32_e32 v4, v8, v4
	v_add_f32_e32 v8, v13, v37
	v_mul_f32_e32 v4, v4, v8
	v_cvt_pk_bf16_f32 v4, v4, s0
	flat_store_short v[2:3], v4 offset:2208 nt
	v_lshlrev_b32_e32 v4, 16, v178
	v_mul_f32_e32 v8, 0x3d372713, v4
	v_mul_f32_e32 v8, v8, v4
	v_fma_f32 v8, v8, v4, v4
	v_mul_f32_e32 v8, 0xbfcc422a, v8
	v_mul_f32_e32 v8, 0x3fb8aa3b, v8
	v_exp_f32_e32 v8, v8
	s_nop 0
	v_add_f32_e32 v8, 1.0, v8
	v_rcp_f32_e32 v8, v8
	s_nop 0
	v_mul_f32_e32 v4, v8, v4
	v_add_f32_e32 v8, v9, v37
	v_mul_f32_e32 v4, v4, v8
	v_cvt_pk_bf16_f32 v4, v4, s0
	flat_store_short v[2:3], v4 offset:2240 nt
	v_lshlrev_b32_e32 v2, 16, v177
	v_mul_f32_e32 v3, 0x3d372713, v2
	v_mul_f32_e32 v3, v3, v2
	v_fma_f32 v3, v3, v2, v2
	v_mul_f32_e32 v3, 0xbfcc422a, v3
	v_mul_f32_e32 v3, 0x3fb8aa3b, v3
	v_exp_f32_e32 v3, v3
	s_nop 0
	v_add_f32_e32 v3, 1.0, v3
	v_rcp_f32_e32 v3, v3
	s_nop 0
	v_mul_f32_e32 v2, v3, v2
	v_add_f32_e32 v3, v5, v37
	v_mul_f32_e32 v2, v2, v3
	v_cvt_pk_bf16_f32 v2, v2, s0
	flat_store_short v[6:7], v2 offset:2048 nt
	s_cbranch_scc1 .LBB0_117
